# v9 + attention unit prologue: score-bound loads issued with the Q loads, DPP max reductions instead of 24 ds_bpermute
# speedup vs baseline: 1.0035x; 1.0035x over previous
.LBB0_556:
	s_or_b64 exec, exec, s[60:61]
	s_lshl_b64 s[60:61], s[56:57], 18
	v_readlane_b32 s1, v246, 39
	s_add_u32 s1, s1, s44
	v_readlane_b32 s44, v246, 40
	s_addc_u32 s44, s44, s45
	s_add_u32 s1, s1, s48
	s_addc_u32 s48, s44, s49
	s_lshl_b64 s[44:45], s[60:61], 2
	v_readlane_b32 s49, v246, 51
	s_add_u32 s44, s49, s44
	v_readlane_b32 s49, v246, 52
	s_addc_u32 s45, s49, s45
	s_lshl_b32 s81, s62, 8
	s_add_i32 s52, s81, s71
	v_or_b32_e32 v0, s52, v170
	v_mov_b32_e32 v1, v153
	v_lshlrev_b64 v[0:1], 7, v[0:1]
	v_lshl_add_u64 v[0:1], s[44:45], 0, v[0:1]
	v_lshl_add_u64 v[12:13], v[146:147], 2, v[0:1]
	s_mul_i32 s44, s52, 0x900
	s_mov_b32 s98, s0
	s_ashr_i32 s99, s0, 31
	s_lshl_b64 s[98:99], s[98:99], 9
	s_lshl_b32 s100, s56, 7
	s_ashr_i32 s101, s100, 31
	v_lshl_add_u64 v[250:251], v[162:163], 0, s[98:99]
	v_lshl_add_u64 v[252:253], s[100:101], 2, v[164:165]
	global_load_dword v247, v[250:251], off
	global_load_dword v248, v[250:251], off offset:256
	global_load_dword v249, v[252:253], off
	global_load_dword v254, v[252:253], off offset:256
	global_load_dwordx4 v[0:3], v[12:13], off
	global_load_dwordx4 v[4:7], v[12:13], off offset:16
	s_mul_hi_u32 s45, s52, 0x900
	global_load_dwordx4 v[8:11], v[12:13], off offset:48
	s_nop 0
	global_load_dwordx4 v[12:15], v[12:13], off offset:32
	s_add_u32 s44, s1, s44
	s_addc_u32 s45, s48, s45
	v_lshl_add_u64 v[16:17], s[44:45], 0, v[152:153]
	v_lshl_add_u64 v[24:25], v[150:151], 1, v[16:17]
	global_load_dwordx4 v[16:19], v[24:25], off offset:128
	global_load_dwordx4 v[20:23], v[24:25], off offset:160
	global_load_dwordx4 v[116:119], v[24:25], off
	global_load_dwordx4 v[112:115], v[24:25], off offset:32
	global_load_dwordx4 v[104:107], v[24:25], off offset:64
	global_load_dwordx4 v[96:99], v[24:25], off offset:96
	v_readlane_b32 s44, v246, 58
	v_readlane_b32 s45, v246, 59
	s_andn2_b64 vcc, exec, s[44:45]
	s_waitcnt vmcnt(9)
	v_mov_b32_e32 v24, v0
	v_mov_b32_e32 v25, v2
	v_mov_b32_e32 v2, v1
	s_waitcnt vmcnt(8)
	v_mov_b32_e32 v0, v4
	v_mov_b32_e32 v1, v6
	v_mov_b32_e32 v6, v5
	s_waitcnt vmcnt(6)
	v_mov_b32_e32 v4, v12
	v_mov_b32_e32 v5, v14
	v_mov_b32_e32 v14, v13
	v_mov_b32_e32 v12, v8
	v_mov_b32_e32 v13, v10
	v_mov_b32_e32 v10, v9
	s_waitcnt vmcnt(5)
	v_and_b32_e32 v9, 0xffff0000, v16
	v_lshlrev_b32_e32 v8, 16, v16
	s_waitcnt vmcnt(4)
	v_and_b32_e32 v27, 0xffff0000, v20
	v_lshlrev_b32_e32 v26, 16, v20
	v_and_b32_e32 v29, 0xffff0000, v17
	v_lshlrev_b32_e32 v28, 16, v17
	v_and_b32_e32 v17, 0xffff0000, v21
	v_lshlrev_b32_e32 v16, 16, v21
	v_and_b32_e32 v21, 0xffff0000, v18
	v_lshlrev_b32_e32 v20, 16, v18
	v_and_b32_e32 v31, 0xffff0000, v22
	v_lshlrev_b32_e32 v30, 16, v22
	v_and_b32_e32 v33, 0xffff0000, v19
	v_lshlrev_b32_e32 v32, 16, v19
	v_and_b32_e32 v19, 0xffff0000, v23
	v_lshlrev_b32_e32 v18, 16, v23
	v_pk_mul_f32 v[22:23], v[2:3], v[26:27]
	v_pk_mul_f32 v[26:27], v[24:25], v[26:27]
	v_pk_mul_f32 v[34:35], v[6:7], v[16:17]
	v_pk_mul_f32 v[16:17], v[0:1], v[16:17]
	v_pk_mul_f32 v[36:37], v[14:15], v[30:31]
	v_pk_mul_f32 v[30:31], v[4:5], v[30:31]
	v_pk_mul_f32 v[38:39], v[10:11], v[18:19]
	v_pk_mul_f32 v[18:19], v[12:13], v[18:19]
	v_pk_fma_f32 v[22:23], v[24:25], v[8:9], v[22:23] neg_lo:[0,0,1] neg_hi:[0,0,1]
	v_pk_fma_f32 v[2:3], v[2:3], v[8:9], v[26:27]
	v_pk_fma_f32 v[0:1], v[0:1], v[28:29], v[34:35] neg_lo:[0,0,1] neg_hi:[0,0,1]
	v_pk_fma_f32 v[6:7], v[6:7], v[28:29], v[16:17]
	v_pk_fma_f32 v[4:5], v[4:5], v[20:21], v[36:37] neg_lo:[0,0,1] neg_hi:[0,0,1]
	v_pk_fma_f32 v[8:9], v[14:15], v[20:21], v[30:31]
	v_pk_fma_f32 v[12:13], v[12:13], v[32:33], v[38:39] neg_lo:[0,0,1] neg_hi:[0,0,1]
	v_pk_fma_f32 v[10:11], v[10:11], v[32:33], v[18:19]
	v_cvt_pk_bf16_f32 v108, v22, v23
	v_cvt_pk_bf16_f32 v109, v0, v1
	v_cvt_pk_bf16_f32 v110, v4, v5
	v_cvt_pk_bf16_f32 v111, v12, v13
	v_cvt_pk_bf16_f32 v100, v2, v3
	v_cvt_pk_bf16_f32 v101, v6, v7
	v_cvt_pk_bf16_f32 v102, v8, v9
	v_cvt_pk_bf16_f32 v103, v10, v11
	s_cbranch_vccnz .LBB0_558
	s_waitcnt vmcnt(3)
	v_lshlrev_b32_e32 v0, 16, v116
	v_fma_f32 v0, v0, v0, 0
	v_and_b32_e32 v1, 0xffff0000, v116
	v_fmac_f32_e32 v0, v1, v1
	v_lshlrev_b32_e32 v1, 16, v117
	v_fmac_f32_e32 v0, v1, v1
	v_and_b32_e32 v1, 0xffff0000, v117
	v_fmac_f32_e32 v0, v1, v1
	v_lshlrev_b32_e32 v1, 16, v118
	v_fmac_f32_e32 v0, v1, v1
	v_and_b32_e32 v1, 0xffff0000, v118
	v_fmac_f32_e32 v0, v1, v1
	v_lshlrev_b32_e32 v1, 16, v119
	v_fmac_f32_e32 v0, v1, v1
	v_and_b32_e32 v1, 0xffff0000, v119
	v_fmac_f32_e32 v0, v1, v1
	s_waitcnt vmcnt(2)
	v_lshlrev_b32_e32 v1, 16, v112
	v_fmac_f32_e32 v0, v1, v1
	v_and_b32_e32 v1, 0xffff0000, v112
	v_fmac_f32_e32 v0, v1, v1
	v_lshlrev_b32_e32 v1, 16, v113
	v_fmac_f32_e32 v0, v1, v1
	v_and_b32_e32 v1, 0xffff0000, v113
	v_fmac_f32_e32 v0, v1, v1
	v_lshlrev_b32_e32 v1, 16, v114
	v_fmac_f32_e32 v0, v1, v1
	v_and_b32_e32 v1, 0xffff0000, v114
	v_fmac_f32_e32 v0, v1, v1
	v_lshlrev_b32_e32 v1, 16, v115
	v_fmac_f32_e32 v0, v1, v1
	v_and_b32_e32 v1, 0xffff0000, v115
	v_fmac_f32_e32 v0, v1, v1
	s_waitcnt vmcnt(1)
	v_lshlrev_b32_e32 v1, 16, v104
	v_fmac_f32_e32 v0, v1, v1
	v_and_b32_e32 v1, 0xffff0000, v104
	v_fmac_f32_e32 v0, v1, v1
	v_lshlrev_b32_e32 v1, 16, v105
	v_fmac_f32_e32 v0, v1, v1
	v_and_b32_e32 v1, 0xffff0000, v105
	v_fmac_f32_e32 v0, v1, v1
	v_lshlrev_b32_e32 v1, 16, v106
	v_fmac_f32_e32 v0, v1, v1
	v_and_b32_e32 v1, 0xffff0000, v106
	v_fmac_f32_e32 v0, v1, v1
	v_lshlrev_b32_e32 v1, 16, v107
	v_fmac_f32_e32 v0, v1, v1
	v_and_b32_e32 v1, 0xffff0000, v107
	v_fmac_f32_e32 v0, v1, v1
	s_waitcnt vmcnt(0)
	v_lshlrev_b32_e32 v1, 16, v96
	v_fmac_f32_e32 v0, v1, v1
	v_and_b32_e32 v1, 0xffff0000, v96
	v_fmac_f32_e32 v0, v1, v1
	v_lshlrev_b32_e32 v1, 16, v97
	v_fmac_f32_e32 v0, v1, v1
	v_and_b32_e32 v1, 0xffff0000, v97
	v_fmac_f32_e32 v0, v1, v1
	v_lshlrev_b32_e32 v1, 16, v98
	v_fmac_f32_e32 v0, v1, v1
	v_and_b32_e32 v1, 0xffff0000, v98
	v_fmac_f32_e32 v0, v1, v1
	v_lshlrev_b32_e32 v1, 16, v99
	v_fmac_f32_e32 v0, v1, v1
	v_and_b32_e32 v1, 0xffff0000, v99
	v_fmac_f32_e32 v0, v1, v1
	v_lshlrev_b32_e32 v1, 16, v108
	v_fmac_f32_e32 v0, v1, v1
	v_and_b32_e32 v1, 0xffff0000, v108
	v_fmac_f32_e32 v0, v1, v1
	v_lshlrev_b32_e32 v1, 16, v109
	v_fmac_f32_e32 v0, v1, v1
	v_and_b32_e32 v1, 0xffff0000, v109
	v_fmac_f32_e32 v0, v1, v1
	v_lshlrev_b32_e32 v1, 16, v110
	v_fmac_f32_e32 v0, v1, v1
	v_and_b32_e32 v1, 0xffff0000, v110
	v_fmac_f32_e32 v0, v1, v1
	v_lshlrev_b32_e32 v1, 16, v111
	v_fmac_f32_e32 v0, v1, v1
	v_and_b32_e32 v1, 0xffff0000, v111
	v_fmac_f32_e32 v0, v1, v1
	v_lshlrev_b32_e32 v1, 16, v100
	v_fmac_f32_e32 v0, v1, v1
	v_and_b32_e32 v1, 0xffff0000, v100
	v_fmac_f32_e32 v0, v1, v1
	v_lshlrev_b32_e32 v1, 16, v101
	v_fmac_f32_e32 v0, v1, v1
	v_and_b32_e32 v1, 0xffff0000, v101
	v_fmac_f32_e32 v0, v1, v1
	v_lshlrev_b32_e32 v1, 16, v102
	v_fmac_f32_e32 v0, v1, v1
	v_and_b32_e32 v1, 0xffff0000, v102
	v_fmac_f32_e32 v0, v1, v1
	v_lshlrev_b32_e32 v1, 16, v103
	v_fmac_f32_e32 v0, v1, v1
	v_and_b32_e32 v1, 0xffff0000, v103
	s_ashr_i32 s1, s0, 31
	v_fmac_f32_e32 v0, v1, v1
	s_lshl_b64 s[0:1], s[0:1], 9
	s_lshl_b32 s44, s56, 7
	v_mov_b32_e32 v1, v0
	s_ashr_i32 s45, s44, 31
	s_nop 0
	v_permlane32_swap_b32_e32 v0, v1
	v_add_f32_e32 v0, v0, v1
	s_mov_b32 s0, 0x45610000
	v_max_f32_e32 v0, v0, v0
	v_max_f32_e32 v1, v247, v247
	v_max_f32_e32 v4, v248, v248
	v_max_f32_e32 v3, v249, v249
	v_max_f32_e32 v2, v254, v254
	s_nop 0
	v_max_f32_e32 v2, v3, v2
	s_nop 1
	v_max_f32_dpp v0, v0, v0 quad_perm:[1,0,3,2] row_mask:0xf bank_mask:0xf
	v_max_f32_dpp v1, v1, v1 quad_perm:[1,0,3,2] row_mask:0xf bank_mask:0xf
	v_max_f32_dpp v4, v4, v4 quad_perm:[1,0,3,2] row_mask:0xf bank_mask:0xf
	v_max_f32_dpp v2, v2, v2 quad_perm:[1,0,3,2] row_mask:0xf bank_mask:0xf
	v_max_f32_dpp v0, v0, v0 quad_perm:[2,3,0,1] row_mask:0xf bank_mask:0xf
	v_max_f32_dpp v1, v1, v1 quad_perm:[2,3,0,1] row_mask:0xf bank_mask:0xf
	v_max_f32_dpp v4, v4, v4 quad_perm:[2,3,0,1] row_mask:0xf bank_mask:0xf
	v_max_f32_dpp v2, v2, v2 quad_perm:[2,3,0,1] row_mask:0xf bank_mask:0xf
	v_max_f32_dpp v0, v0, v0 row_half_mirror row_mask:0xf bank_mask:0xf
	v_max_f32_dpp v1, v1, v1 row_half_mirror row_mask:0xf bank_mask:0xf
	v_max_f32_dpp v4, v4, v4 row_half_mirror row_mask:0xf bank_mask:0xf
	v_max_f32_dpp v2, v2, v2 row_half_mirror row_mask:0xf bank_mask:0xf
	v_max_f32_dpp v0, v0, v0 row_mirror row_mask:0xf bank_mask:0xf
	v_max_f32_dpp v1, v1, v1 row_mirror row_mask:0xf bank_mask:0xf
	v_max_f32_dpp v4, v4, v4 row_mirror row_mask:0xf bank_mask:0xf
	v_max_f32_dpp v2, v2, v2 row_mirror row_mask:0xf bank_mask:0xf
	v_max_f32_dpp v0, v0, v0 row_bcast:15 row_mask:0xa bank_mask:0xf
	v_max_f32_dpp v1, v1, v1 row_bcast:15 row_mask:0xa bank_mask:0xf
	v_max_f32_dpp v4, v4, v4 row_bcast:15 row_mask:0xa bank_mask:0xf
	v_max_f32_dpp v2, v2, v2 row_bcast:15 row_mask:0xa bank_mask:0xf
	v_max_f32_dpp v0, v0, v0 row_bcast:31 row_mask:0xc bank_mask:0xf
	v_max_f32_dpp v1, v1, v1 row_bcast:31 row_mask:0xc bank_mask:0xf
	v_max_f32_dpp v4, v4, v4 row_bcast:31 row_mask:0xc bank_mask:0xf
	v_max_f32_dpp v2, v2, v2 row_bcast:31 row_mask:0xc bank_mask:0xf
	v_add_f32_e32 v1, v1, v4
	v_add_f32_e32 v1, v2, v1
	v_mul_f32_e32 v0, v0, v1
	v_mul_f32_e32 v0, 0x3f866666, v0
	v_cmp_ge_f32_e32 vcc, s0, v0
	s_nop 1
	v_cndmask_b32_e64 v0, 0, 1, vcc
	s_nop 0
	v_readlane_b32 s0, v0, 63
	s_bitcmp1_b32 s0, 0
	s_cselect_b64 s[44:45], -1, 0
	s_branch .LBB0_559

	.amdhsa_kernel _Z8mega_fwd4Args
		.amdhsa_group_segment_fixed_size 0
		.amdhsa_private_segment_fixed_size 0
		.amdhsa_kernarg_size 448
		.amdhsa_user_sgpr_count 2
		.amdhsa_user_sgpr_dispatch_ptr 0
		.amdhsa_user_sgpr_queue_ptr 0
		.amdhsa_user_sgpr_kernarg_segment_ptr 1
		.amdhsa_user_sgpr_dispatch_id 0
		.amdhsa_user_sgpr_kernarg_preload_length 0
		.amdhsa_user_sgpr_kernarg_preload_offset 0
		.amdhsa_user_sgpr_private_segment_size 0
		.amdhsa_uses_dynamic_stack 0
		.amdhsa_enable_private_segment 0
		.amdhsa_system_sgpr_workgroup_id_x 1
		.amdhsa_system_sgpr_workgroup_id_y 0
		.amdhsa_system_sgpr_workgroup_id_z 0
		.amdhsa_system_sgpr_workgroup_info 0
		.amdhsa_system_vgpr_workitem_id 0
		.amdhsa_next_free_vgpr 256
		.amdhsa_next_free_sgpr 102
		.amdhsa_accum_offset 256
		.amdhsa_reserve_vcc 1
		.amdhsa_float_round_mode_32 0
		.amdhsa_float_round_mode_16_64 0
		.amdhsa_float_denorm_mode_32 3
		.amdhsa_float_denorm_mode_16_64 3
		.amdhsa_dx10_clamp 1
		.amdhsa_ieee_mode 1
		.amdhsa_fp16_overflow 0
		.amdhsa_tg_split 0
		.amdhsa_exception_fp_ieee_invalid_op 0
		.amdhsa_exception_fp_denorm_src 0
		.amdhsa_exception_fp_ieee_div_zero 0
		.amdhsa_exception_fp_ieee_overflow 0
		.amdhsa_exception_fp_ieee_underflow 0
		.amdhsa_exception_fp_ieee_inexact 0
		.amdhsa_exception_int_div_zero 0
	.end_amdhsa_kernel

amdhsa.kernels:
  - .agpr_count:     0
    .args:
      - .offset:         0
        .size:           192
        .value_kind:     by_value
      - .offset:         192
        .size:           4
        .value_kind:     hidden_block_count_x
      - .offset:         196
        .size:           4
        .value_kind:     hidden_block_count_y
      - .offset:         200
        .size:           4
        .value_kind:     hidden_block_count_z
      - .offset:         204
        .size:           2
        .value_kind:     hidden_group_size_x
      - .offset:         206
        .size:           2
        .value_kind:     hidden_group_size_y
      - .offset:         208
        .size:           2
        .value_kind:     hidden_group_size_z
      - .offset:         210
        .size:           2
        .value_kind:     hidden_remainder_x
      - .offset:         212
        .size:           2
        .value_kind:     hidden_remainder_y
      - .offset:         214
        .size:           2
        .value_kind:     hidden_remainder_z
      - .offset:         232
        .size:           8
        .value_kind:     hidden_global_offset_x
      - .offset:         240
        .size:           8
        .value_kind:     hidden_global_offset_y
      - .offset:         248
        .size:           8
        .value_kind:     hidden_global_offset_z
      - .offset:         256
        .size:           2
        .value_kind:     hidden_grid_dims
      - .offset:         312
        .size:           4
        .value_kind:     hidden_dynamic_lds_size
    .group_segment_fixed_size: 0
    .kernarg_segment_align: 8
    .kernarg_segment_size: 448
    .language:       OpenCL C
    .language_version:
      - 2
      - 0
    .max_flat_workgroup_size: 512
    .name:           _Z8mega_fwd4Args
    .private_segment_fixed_size: 0
    .sgpr_count:     108
    .sgpr_spill_count: 151
    .symbol:         _Z8mega_fwd4Args.kd
    .uniform_work_group_size: 1
    .uses_dynamic_stack: false
    .vgpr_count:     256
    .vgpr_spill_count: 0
    .wavefront_size: 64
